# FFN epilogue: dead zero-inits of DPP destinations removed (hazard-guarded) + attention/norm LDS pipelining + gemm1 sc1 stores
# baseline (speedup 1.0000x reference)
; __device__ __forceinline__ u32x4 pack8(const float (&f)[8]) { u32x4 w; w.x = cvt_pk_bf16(f[0], f[1]); w.y = cvt_pk_bf16(f[2], f[3]); w.z = cvt_pk_bf16(f[4], f[5]); w.w = cvt_pk_bf16(f[6], f[7]); return w; }
; __device__ __forceinline__ float dpp_row_shr1(float x) { return __int_as_float(__builtin_amdgcn_update_dpp(0, __float_as_int(x), 0x111, 0xf, 0xf, false)); }
; __device__ __forceinline__ float dpp_row_shr2(float x) { return __int_as_float(__builtin_amdgcn_update_dpp(0, __float_as_int(x), 0x112, 0xf, 0xf, false)); }
; __device__ __forceinline__ float dpp_row_ror1(float x) { return __int_as_float(__builtin_amdgcn_update_dpp(0, __float_as_int(x), 0x121, 0xf, 0xf, false)); }
; __device__ __forceinline__ f32x2 gelu_tanh_mul2(f32x2 gt, f32x2 up) {
;     const f32x2 g2 = gt * gt;
;     const f32x2 t = gt * (g2 * 0.044715f + 1.0f);
;     const f32x2 sx = t * (-2.0f * 0.7978845608028654f * 1.4426950408889634f);
;     f32x2 e; e.x = __builtin_amdgcn_exp2f(sx.x); e.y = __builtin_amdgcn_exp2f(sx.y);
;     const f32x2 d = e + 1.0f;
;     f32x2 r; r.x = __builtin_amdgcn_rcpf(d.x); r.y = __builtin_amdgcn_rcpf(d.y);
;     return gt * r * up;
; }
;     __device__ __forceinline__ void operator()(const f32x4 (&acc)[2][2][4][2], const Unit& u, int wr, int wc, int fr, int fq) const {
;     ...
;                     float p1a[8], p2a[8];
; #pragma unroll
;                     for (int e = 0; e < 8; ++e) { const float pv = (e < 4) ? acc[ai][0][m - 1][0][e & 3] : acc[ai][0][m - 1][1][e & 3];
;                         const float s1 = dpp_row_shr1(g8[e]), s2 = dpp_row_shr2(g8[e]), r1 = dpp_row_ror1(pv), r2 = dpp_row_ror2(pv);
;                         p1a[e] = (fr >= 1) ? s1 : r1; p2a[e] = (fr >= 2) ? s2 : r2; }
; #pragma unroll
;                     for (int e = 0; e < 8; e += 2) { const f32x2 gt = (f32x2){w0[e], w0[e + 1]} * (f32x2){p2a[e], p2a[e + 1]} + (f32x2){w1[e], w1[e + 1]} * (f32x2){p1a[e], p1a[e + 1]} + (f32x2){w2[e], w2[e + 1]} * (f32x2){g8[e], g8[e + 1]} + (f32x2){bb[e], bb[e + 1]};
;                         const f32x2 r = gelu_tanh_mul2(gt, (f32x2){u8[e], u8[e + 1]}); o[e] = r.x; o[e + 1] = r.y; }
;                 }
;                 const int rloc = 128 * ai + 64 * wr + 16 * m + fr;
;                 if (!(B == 0 && m == 0 && fr < 2)) *(u32x4*)(ACT + (size_t)(u.pm * BM + rloc) * FF + chg) = pack8(o);
.LBB0_84:
	s_andn2_saveexec_b64 s[30:31], s[30:31]
	s_or_b64 exec, exec, s[30:31]
	s_nop 0
	s_nop 0
	v_mov_b32_dpp v154, v134 row_shr:1 row_mask:0xf bank_mask:0xf bound_ctrl:0
	v_mov_b32_dpp v155, v134 row_shr:2 row_mask:0xf bank_mask:0xf bound_ctrl:0
	v_mov_b32_dpp v156, v150 row_ror:1 row_mask:0xf bank_mask:0xf
	v_mov_b32_dpp v157, v150 row_ror:2 row_mask:0xf bank_mask:0xf
	v_cndmask_b32_e64 v150, v154, v156, s[40:41]
	v_cndmask_b32_e64 v154, v157, v155, s[38:39]
	v_mov_b32_dpp v155, v135 row_shr:1 row_mask:0xf bank_mask:0xf bound_ctrl:0
	v_mov_b32_dpp v156, v135 row_shr:2 row_mask:0xf bank_mask:0xf bound_ctrl:0
	v_mov_b32_dpp v157, v151 row_ror:1 row_mask:0xf bank_mask:0xf
	v_mov_b32_dpp v158, v151 row_ror:2 row_mask:0xf bank_mask:0xf
	v_cndmask_b32_e64 v151, v155, v157, s[40:41]
	v_cndmask_b32_e64 v155, v158, v156, s[38:39]
	v_mov_b32_dpp v156, v136 row_shr:1 row_mask:0xf bank_mask:0xf bound_ctrl:0
	v_mov_b32_dpp v157, v136 row_shr:2 row_mask:0xf bank_mask:0xf bound_ctrl:0
	v_mov_b32_dpp v158, v152 row_ror:1 row_mask:0xf bank_mask:0xf
	v_mov_b32_dpp v159, v152 row_ror:2 row_mask:0xf bank_mask:0xf
	v_cndmask_b32_e64 v152, v156, v158, s[40:41]
	v_cndmask_b32_e64 v156, v159, v157, s[38:39]
	v_mov_b32_dpp v157, v137 row_shr:1 row_mask:0xf bank_mask:0xf bound_ctrl:0
	v_mov_b32_dpp v158, v137 row_shr:2 row_mask:0xf bank_mask:0xf bound_ctrl:0
	v_mov_b32_dpp v159, v153 row_ror:1 row_mask:0xf bank_mask:0xf
	v_mov_b32_dpp v160, v153 row_ror:2 row_mask:0xf bank_mask:0xf
	v_cndmask_b32_e64 v153, v157, v159, s[40:41]
	v_cndmask_b32_e64 v157, v160, v158, s[38:39]
	s_waitcnt vmcnt(0)
	v_pk_mul_f32 v[154:155], v[90:91], v[154:155]
	v_pk_mul_f32 v[156:157], v[92:93], v[156:157]
	v_pk_fma_f32 v[150:151], v[94:95], v[150:151], v[154:155]
	v_pk_fma_f32 v[152:153], v[96:97], v[152:153], v[156:157]
	v_pk_fma_f32 v[150:151], v[134:135], v[98:99], v[150:151]
	v_pk_fma_f32 v[152:153], v[136:137], v[100:101], v[152:153]
	v_pk_add_f32 v[150:151], v[102:103], v[150:151]
	v_pk_add_f32 v[152:153], v[104:105], v[152:153]
	v_pk_mul_f32 v[154:155], v[150:151], v[150:151]
	v_pk_mul_f32 v[156:157], v[152:153], v[152:153]
	v_pk_fma_f32 v[154:155], v[154:155], s[78:79], 1.0 op_sel_hi:[1,0,0]
	v_pk_fma_f32 v[156:157], v[156:157], s[78:79], 1.0 op_sel_hi:[1,0,0]
	v_pk_mul_f32 v[154:155], v[150:151], v[154:155]
	v_pk_mul_f32 v[156:157], v[152:153], v[156:157]
	v_pk_mul_f32 v[154:155], v[154:155], s[24:25] op_sel_hi:[1,0]
	v_pk_mul_f32 v[156:157], v[156:157], s[24:25] op_sel_hi:[1,0]
	v_exp_f32_e32 v154, v154
	v_exp_f32_e32 v155, v155
	v_exp_f32_e32 v156, v156
	v_exp_f32_e32 v157, v157
	v_mov_b32_dpp v158, v130 row_shr:1 row_mask:0xf bank_mask:0xf bound_ctrl:0
	v_mov_b32_dpp v159, v130 row_shr:2 row_mask:0xf bank_mask:0xf bound_ctrl:0
	v_mov_b32_dpp v160, v146 row_ror:1 row_mask:0xf bank_mask:0xf
	v_mov_b32_dpp v161, v146 row_ror:2 row_mask:0xf bank_mask:0xf
	v_cndmask_b32_e64 v146, v158, v160, s[40:41]
	v_cndmask_b32_e64 v158, v161, v159, s[38:39]
	s_waitcnt lgkmcnt(3)
	v_pk_add_f32 v[154:155], v[154:155], 1.0 op_sel_hi:[1,0]
	v_mov_b32_dpp v159, v131 row_shr:1 row_mask:0xf bank_mask:0xf bound_ctrl:0
	v_mov_b32_dpp v160, v131 row_shr:2 row_mask:0xf bank_mask:0xf bound_ctrl:0
	v_mov_b32_dpp v161, v147 row_ror:1 row_mask:0xf bank_mask:0xf
	v_mov_b32_dpp v162, v147 row_ror:2 row_mask:0xf bank_mask:0xf
	v_rcp_f32_e32 v154, v154
	v_rcp_f32_e32 v155, v155
	v_pk_add_f32 v[156:157], v[156:157], 1.0 op_sel_hi:[1,0]
	v_cndmask_b32_e64 v147, v159, v161, s[40:41]
	v_cndmask_b32_e64 v159, v162, v160, s[38:39]
	v_rcp_f32_e32 v156, v156
	v_rcp_f32_e32 v157, v157
	v_mov_b32_dpp v160, v132 row_shr:1 row_mask:0xf bank_mask:0xf bound_ctrl:0
	v_mov_b32_dpp v161, v132 row_shr:2 row_mask:0xf bank_mask:0xf bound_ctrl:0
	v_mov_b32_dpp v162, v148 row_ror:1 row_mask:0xf bank_mask:0xf
	v_mov_b32_dpp v163, v148 row_ror:2 row_mask:0xf bank_mask:0xf
	v_cndmask_b32_e64 v148, v160, v162, s[40:41]
	v_cndmask_b32_e64 v160, v163, v161, s[38:39]
	v_mov_b32_dpp v161, v133 row_shr:1 row_mask:0xf bank_mask:0xf bound_ctrl:0
	v_mov_b32_dpp v162, v133 row_shr:2 row_mask:0xf bank_mask:0xf bound_ctrl:0
	v_mov_b32_dpp v163, v149 row_ror:1 row_mask:0xf bank_mask:0xf
	v_mov_b32_dpp v164, v149 row_ror:2 row_mask:0xf bank_mask:0xf
	v_pk_mul_f32 v[150:151], v[150:151], v[154:155]
	v_cndmask_b32_e64 v149, v161, v163, s[40:41]
	v_cndmask_b32_e64 v161, v164, v162, s[38:39]
	v_pk_mul_f32 v[142:143], v[142:143], v[150:151]
	v_pk_mul_f32 v[150:151], v[152:153], v[156:157]
	v_pk_mul_f32 v[152:153], v[66:67], v[158:159]
	v_pk_mul_f32 v[154:155], v[68:69], v[160:161]
	v_pk_fma_f32 v[146:147], v[70:71], v[146:147], v[152:153]
	v_pk_fma_f32 v[148:149], v[72:73], v[148:149], v[154:155]
	v_pk_fma_f32 v[146:147], v[130:131], v[74:75], v[146:147]
	v_pk_fma_f32 v[148:149], v[132:133], v[76:77], v[148:149]
	v_pk_add_f32 v[146:147], v[78:79], v[146:147]
	v_pk_add_f32 v[148:149], v[80:81], v[148:149]
	v_pk_mul_f32 v[152:153], v[146:147], v[146:147]
	v_pk_mul_f32 v[154:155], v[148:149], v[148:149]
	v_pk_fma_f32 v[152:153], v[152:153], s[78:79], 1.0 op_sel_hi:[1,0,0]
	v_pk_fma_f32 v[154:155], v[154:155], s[78:79], 1.0 op_sel_hi:[1,0,0]
	v_pk_mul_f32 v[152:153], v[146:147], v[152:153]
	v_pk_mul_f32 v[154:155], v[148:149], v[154:155]
	v_pk_mul_f32 v[152:153], v[152:153], s[24:25] op_sel_hi:[1,0]
	v_pk_mul_f32 v[154:155], v[154:155], s[24:25] op_sel_hi:[1,0]
	v_exp_f32_e32 v152, v152
	v_exp_f32_e32 v153, v153
	v_exp_f32_e32 v154, v154
	v_exp_f32_e32 v155, v155
	v_readlane_b32 s8, v253, 57
	v_pk_add_f32 v[152:153], v[152:153], 1.0 op_sel_hi:[1,0]
	v_pk_mul_f32 v[144:145], v[144:145], v[150:151]
	v_rcp_f32_e32 v152, v152
	v_rcp_f32_e32 v153, v153
; __device__ __forceinline__ u32x4 pack8(const float (&f)[8]) { u32x4 w; w.x = cvt_pk_bf16(f[0], f[1]); w.y = cvt_pk_bf16(f[2], f[3]); w.z = cvt_pk_bf16(f[4], f[5]); w.w = cvt_pk_bf16(f[6], f[7]); return w; }
; __device__ __forceinline__ float dpp_row_shr1(float x) { return __int_as_float(__builtin_amdgcn_update_dpp(0, __float_as_int(x), 0x111, 0xf, 0xf, false)); }
; __device__ __forceinline__ float dpp_row_shr2(float x) { return __int_as_float(__builtin_amdgcn_update_dpp(0, __float_as_int(x), 0x112, 0xf, 0xf, false)); }
; __device__ __forceinline__ float dpp_row_ror1(float x) { return __int_as_float(__builtin_amdgcn_update_dpp(0, __float_as_int(x), 0x121, 0xf, 0xf, false)); }
; __device__ __forceinline__ f32x2 gelu_tanh_mul2(f32x2 gt, f32x2 up) {
;     const f32x2 g2 = gt * gt;
;     const f32x2 t = gt * (g2 * 0.044715f + 1.0f);
;     const f32x2 sx = t * (-2.0f * 0.7978845608028654f * 1.4426950408889634f);
;     f32x2 e; e.x = __builtin_amdgcn_exp2f(sx.x); e.y = __builtin_amdgcn_exp2f(sx.y);
;     const f32x2 d = e + 1.0f;
;     f32x2 r; r.x = __builtin_amdgcn_rcpf(d.x); r.y = __builtin_amdgcn_rcpf(d.y);
;     return gt * r * up;
; }
;     __device__ __forceinline__ void operator()(const f32x4 (&acc)[2][2][4][2], const Unit& u, int wr, int wc, int fr, int fq) const {
;     ...
;                     float p1a[8], p2a[8];
; #pragma unroll
;                     for (int e = 0; e < 8; ++e) { const float pv = (e < 4) ? acc[ai][0][m - 1][0][e & 3] : acc[ai][0][m - 1][1][e & 3];
;                         const float s1 = dpp_row_shr1(g8[e]), s2 = dpp_row_shr2(g8[e]), r1 = dpp_row_ror1(pv), r2 = dpp_row_ror2(pv);
;                         p1a[e] = (fr >= 1) ? s1 : r1; p2a[e] = (fr >= 2) ? s2 : r2; }
; #pragma unroll
;                     for (int e = 0; e < 8; e += 2) { const f32x2 gt = (f32x2){w0[e], w0[e + 1]} * (f32x2){p2a[e], p2a[e + 1]} + (f32x2){w1[e], w1[e + 1]} * (f32x2){p1a[e], p1a[e + 1]} + (f32x2){w2[e], w2[e + 1]} * (f32x2){g8[e], g8[e + 1]} + (f32x2){bb[e], bb[e + 1]};
;                         const f32x2 r = gelu_tanh_mul2(gt, (f32x2){u8[e], u8[e + 1]}); o[e] = r.x; o[e + 1] = r.y; }
;                 }
;                 const int rloc = 128 * ai + 64 * wr + 16 * m + fr;
;                 if (!(B == 0 && m == 0 && fr < 2)) *(u32x4*)(ACT + (size_t)(u.pm * BM + rloc) * FF + chg) = pack8(o);
	v_pk_add_f32 v[154:155], v[154:155], 1.0 op_sel_hi:[1,0]
	v_readlane_b32 s9, v253, 58
	v_rcp_f32_e32 v154, v154
	v_rcp_f32_e32 v155, v155
	v_pk_mul_f32 v[146:147], v[146:147], v[152:153]
	v_cvt_pk_bf16_f32 v142, v142, v143
	v_cvt_pk_bf16_f32 v143, v144, v145
	s_movk_i32 s7, 0x1600
	v_pk_mul_f32 v[138:139], v[138:139], v[146:147]
	v_pk_mul_f32 v[146:147], v[148:149], v[154:155]
	v_cvt_pk_bf16_f32 v144, v138, v139
	v_or_b32_e32 v138, 16, v210
	v_pk_mul_f32 v[140:141], v[140:141], v[146:147]
	v_mov_b32_e32 v148, v195
	v_cvt_pk_bf16_f32 v145, v140, v141
	v_mov_b64_e32 v[140:141], s[8:9]
	v_mad_i64_i32 v[146:147], s[8:9], v138, s7, v[140:141]
	v_lshlrev_b64 v[138:139], 1, v[192:193]
	v_lshl_add_u64 v[146:147], v[146:147], 0, v[138:139]
	global_store_dwordx4 v[146:147], v[142:145], off
	s_nop 0
	s_nop 0
	s_nop 0
	s_nop 0
	v_mov_b32_dpp v142, v118 row_shr:1 row_mask:0xf bank_mask:0xf bound_ctrl:0
	v_mov_b32_dpp v143, v118 row_shr:2 row_mask:0xf bank_mask:0xf bound_ctrl:0
	v_mov_b32_dpp v144, v134 row_ror:1 row_mask:0xf bank_mask:0xf
	v_mov_b32_dpp v145, v134 row_ror:2 row_mask:0xf bank_mask:0xf
	v_cndmask_b32_e64 v134, v142, v144, s[40:41]
	v_cndmask_b32_e64 v142, v145, v143, s[38:39]
	v_mov_b32_dpp v143, v119 row_shr:1 row_mask:0xf bank_mask:0xf bound_ctrl:0
	v_mov_b32_dpp v144, v119 row_shr:2 row_mask:0xf bank_mask:0xf bound_ctrl:0
	v_mov_b32_dpp v145, v135 row_ror:1 row_mask:0xf bank_mask:0xf
	v_mov_b32_dpp v146, v135 row_ror:2 row_mask:0xf bank_mask:0xf
	v_cndmask_b32_e64 v135, v143, v145, s[40:41]
	v_cndmask_b32_e64 v143, v146, v144, s[38:39]
	v_mov_b32_dpp v144, v120 row_shr:1 row_mask:0xf bank_mask:0xf bound_ctrl:0
	v_mov_b32_dpp v145, v120 row_shr:2 row_mask:0xf bank_mask:0xf bound_ctrl:0
	v_mov_b32_dpp v146, v136 row_ror:1 row_mask:0xf bank_mask:0xf
	v_mov_b32_dpp v147, v136 row_ror:2 row_mask:0xf bank_mask:0xf
	v_cndmask_b32_e64 v136, v144, v146, s[40:41]
	v_cndmask_b32_e64 v144, v147, v145, s[38:39]
	v_mov_b32_dpp v145, v121 row_shr:1 row_mask:0xf bank_mask:0xf bound_ctrl:0
	v_mov_b32_dpp v146, v121 row_shr:2 row_mask:0xf bank_mask:0xf bound_ctrl:0
	v_mov_b32_dpp v147, v137 row_ror:1 row_mask:0xf bank_mask:0xf
	v_mov_b32_dpp v148, v137 row_ror:2 row_mask:0xf bank_mask:0xf
	v_cndmask_b32_e64 v137, v145, v147, s[40:41]
	v_cndmask_b32_e64 v145, v148, v146, s[38:39]
	v_pk_mul_f32 v[142:143], v[90:91], v[142:143]
	v_pk_mul_f32 v[144:145], v[92:93], v[144:145]
	v_pk_fma_f32 v[134:135], v[94:95], v[134:135], v[142:143]
	v_pk_fma_f32 v[136:137], v[96:97], v[136:137], v[144:145]
	v_pk_fma_f32 v[134:135], v[118:119], v[98:99], v[134:135]
	v_pk_fma_f32 v[136:137], v[120:121], v[100:101], v[136:137]
	v_pk_add_f32 v[134:135], v[102:103], v[134:135]
	v_pk_add_f32 v[136:137], v[104:105], v[136:137]
	v_pk_mul_f32 v[142:143], v[134:135], v[134:135]
	v_pk_mul_f32 v[144:145], v[136:137], v[136:137]
	v_pk_fma_f32 v[142:143], v[142:143], s[78:79], 1.0 op_sel_hi:[1,0,0]
	v_pk_fma_f32 v[144:145], v[144:145], s[78:79], 1.0 op_sel_hi:[1,0,0]
	v_pk_mul_f32 v[142:143], v[134:135], v[142:143]
	v_pk_mul_f32 v[144:145], v[136:137], v[144:145]
	v_pk_mul_f32 v[142:143], v[142:143], s[24:25] op_sel_hi:[1,0]
	v_pk_mul_f32 v[144:145], v[144:145], s[24:25] op_sel_hi:[1,0]
	v_exp_f32_e32 v142, v142
	v_exp_f32_e32 v143, v143
	v_exp_f32_e32 v144, v144
	v_exp_f32_e32 v145, v145
	v_mov_b32_dpp v146, v114 row_shr:1 row_mask:0xf bank_mask:0xf bound_ctrl:0
	v_mov_b32_dpp v147, v114 row_shr:2 row_mask:0xf bank_mask:0xf bound_ctrl:0
	v_mov_b32_dpp v148, v130 row_ror:1 row_mask:0xf bank_mask:0xf
	v_mov_b32_dpp v149, v130 row_ror:2 row_mask:0xf bank_mask:0xf
	v_cndmask_b32_e64 v130, v146, v148, s[40:41]
	v_cndmask_b32_e64 v146, v149, v147, s[38:39]
	v_pk_add_f32 v[142:143], v[142:143], 1.0 op_sel_hi:[1,0]
	v_mov_b32_dpp v147, v115 row_shr:1 row_mask:0xf bank_mask:0xf bound_ctrl:0
	v_mov_b32_dpp v148, v115 row_shr:2 row_mask:0xf bank_mask:0xf bound_ctrl:0
	v_mov_b32_dpp v149, v131 row_ror:1 row_mask:0xf bank_mask:0xf
	v_mov_b32_dpp v150, v131 row_ror:2 row_mask:0xf bank_mask:0xf
	v_rcp_f32_e32 v142, v142
	v_rcp_f32_e32 v143, v143
	v_pk_add_f32 v[144:145], v[144:145], 1.0 op_sel_hi:[1,0]
	v_cndmask_b32_e64 v131, v147, v149, s[40:41]
	v_cndmask_b32_e64 v147, v150, v148, s[38:39]
	v_rcp_f32_e32 v144, v144
	v_rcp_f32_e32 v145, v145
	v_mov_b32_dpp v148, v116 row_shr:1 row_mask:0xf bank_mask:0xf bound_ctrl:0
	v_mov_b32_dpp v149, v116 row_shr:2 row_mask:0xf bank_mask:0xf bound_ctrl:0
	v_mov_b32_dpp v150, v132 row_ror:1 row_mask:0xf bank_mask:0xf
	v_mov_b32_dpp v151, v132 row_ror:2 row_mask:0xf bank_mask:0xf
	v_cndmask_b32_e64 v132, v148, v150, s[40:41]
	v_cndmask_b32_e64 v148, v151, v149, s[38:39]
	v_mov_b32_dpp v149, v117 row_shr:1 row_mask:0xf bank_mask:0xf bound_ctrl:0
	v_mov_b32_dpp v150, v117 row_shr:2 row_mask:0xf bank_mask:0xf bound_ctrl:0
	v_mov_b32_dpp v151, v133 row_ror:1 row_mask:0xf bank_mask:0xf
	v_mov_b32_dpp v152, v133 row_ror:2 row_mask:0xf bank_mask:0xf
	v_pk_mul_f32 v[134:135], v[134:135], v[142:143]
	v_cndmask_b32_e64 v133, v149, v151, s[40:41]
	v_cndmask_b32_e64 v149, v152, v150, s[38:39]
	v_pk_mul_f32 v[126:127], v[126:127], v[134:135]
	v_pk_mul_f32 v[134:135], v[136:137], v[144:145]
	v_pk_mul_f32 v[136:137], v[66:67], v[146:147]
	v_pk_mul_f32 v[142:143], v[68:69], v[148:149]
	v_pk_fma_f32 v[130:131], v[70:71], v[130:131], v[136:137]
	v_pk_fma_f32 v[132:133], v[72:73], v[132:133], v[142:143]
	v_pk_fma_f32 v[130:131], v[114:115], v[74:75], v[130:131]
	v_pk_fma_f32 v[132:133], v[116:117], v[76:77], v[132:133]
	v_pk_add_f32 v[130:131], v[78:79], v[130:131]
	v_pk_add_f32 v[132:133], v[80:81], v[132:133]
	v_pk_mul_f32 v[136:137], v[130:131], v[130:131]
; __device__ __forceinline__ u32x4 pack8(const float (&f)[8]) { u32x4 w; w.x = cvt_pk_bf16(f[0], f[1]); w.y = cvt_pk_bf16(f[2], f[3]); w.z = cvt_pk_bf16(f[4], f[5]); w.w = cvt_pk_bf16(f[6], f[7]); return w; }
; __device__ __forceinline__ float dpp_row_shr1(float x) { return __int_as_float(__builtin_amdgcn_update_dpp(0, __float_as_int(x), 0x111, 0xf, 0xf, false)); }
; __device__ __forceinline__ float dpp_row_shr2(float x) { return __int_as_float(__builtin_amdgcn_update_dpp(0, __float_as_int(x), 0x112, 0xf, 0xf, false)); }
; __device__ __forceinline__ float dpp_row_ror1(float x) { return __int_as_float(__builtin_amdgcn_update_dpp(0, __float_as_int(x), 0x121, 0xf, 0xf, false)); }
; __device__ __forceinline__ f32x2 gelu_tanh_mul2(f32x2 gt, f32x2 up) {
;     const f32x2 g2 = gt * gt;
;     const f32x2 t = gt * (g2 * 0.044715f + 1.0f);
;     const f32x2 sx = t * (-2.0f * 0.7978845608028654f * 1.4426950408889634f);
;     f32x2 e; e.x = __builtin_amdgcn_exp2f(sx.x); e.y = __builtin_amdgcn_exp2f(sx.y);
;     const f32x2 d = e + 1.0f;
;     f32x2 r; r.x = __builtin_amdgcn_rcpf(d.x); r.y = __builtin_amdgcn_rcpf(d.y);
;     return gt * r * up;
; }
;     __device__ __forceinline__ void operator()(const f32x4 (&acc)[2][2][4][2], const Unit& u, int wr, int wc, int fr, int fq) const {
;     ...
;                     float p1a[8], p2a[8];
; #pragma unroll
;                     for (int e = 0; e < 8; ++e) { const float pv = (e < 4) ? acc[ai][0][m - 1][0][e & 3] : acc[ai][0][m - 1][1][e & 3];
;                         const float s1 = dpp_row_shr1(g8[e]), s2 = dpp_row_shr2(g8[e]), r1 = dpp_row_ror1(pv), r2 = dpp_row_ror2(pv);
;                         p1a[e] = (fr >= 1) ? s1 : r1; p2a[e] = (fr >= 2) ? s2 : r2; }
; #pragma unroll
;                     for (int e = 0; e < 8; e += 2) { const f32x2 gt = (f32x2){w0[e], w0[e + 1]} * (f32x2){p2a[e], p2a[e + 1]} + (f32x2){w1[e], w1[e + 1]} * (f32x2){p1a[e], p1a[e + 1]} + (f32x2){w2[e], w2[e + 1]} * (f32x2){g8[e], g8[e + 1]} + (f32x2){bb[e], bb[e + 1]};
;                         const f32x2 r = gelu_tanh_mul2(gt, (f32x2){u8[e], u8[e + 1]}); o[e] = r.x; o[e + 1] = r.y; }
;                 }
;                 const int rloc = 128 * ai + 64 * wr + 16 * m + fr;
;                 if (!(B == 0 && m == 0 && fr < 2)) *(u32x4*)(ACT + (size_t)(u.pm * BM + rloc) * FF + chg) = pack8(o);
	v_pk_mul_f32 v[142:143], v[132:133], v[132:133]
	v_pk_fma_f32 v[136:137], v[136:137], s[78:79], 1.0 op_sel_hi:[1,0,0]
	v_pk_fma_f32 v[142:143], v[142:143], s[78:79], 1.0 op_sel_hi:[1,0,0]
	v_pk_mul_f32 v[136:137], v[130:131], v[136:137]
	v_pk_mul_f32 v[142:143], v[132:133], v[142:143]
	v_pk_mul_f32 v[136:137], v[136:137], s[24:25] op_sel_hi:[1,0]
	v_pk_mul_f32 v[142:143], v[142:143], s[24:25] op_sel_hi:[1,0]
	v_exp_f32_e32 v136, v136
	v_exp_f32_e32 v137, v137
	v_exp_f32_e32 v142, v142
	v_exp_f32_e32 v143, v143
	v_pk_mul_f32 v[128:129], v[128:129], v[134:135]
	v_pk_add_f32 v[136:137], v[136:137], 1.0 op_sel_hi:[1,0]
	s_movk_i32 s10, 0x1600
	v_rcp_f32_e32 v136, v136
	v_rcp_f32_e32 v137, v137
	v_pk_add_f32 v[142:143], v[142:143], 1.0 op_sel_hi:[1,0]
	s_andn2_b64 vcc, exec, s[62:63]
	v_rcp_f32_e32 v142, v142
	v_rcp_f32_e32 v143, v143
	v_pk_mul_f32 v[130:131], v[130:131], v[136:137]
	s_nop 0
	v_pk_mul_f32 v[130:131], v[122:123], v[130:131]
	v_pk_mul_f32 v[122:123], v[132:133], v[142:143]
	s_nop 0
	v_pk_mul_f32 v[132:133], v[124:125], v[122:123]
	v_cvt_pk_bf16_f32 v122, v126, v127
	v_or_b32_e32 v126, 32, v210
	v_mad_i64_i32 v[126:127], s[8:9], v126, s7, v[140:141]
	v_cvt_pk_bf16_f32 v123, v128, v129
	v_cvt_pk_bf16_f32 v124, v130, v131
	v_cvt_pk_bf16_f32 v125, v132, v133
	v_lshl_add_u64 v[126:127], v[126:127], 0, v[138:139]
	global_store_dwordx4 v[126:127], v[122:125], off
	s_nop 0
	s_nop 0
	s_nop 0
	s_nop 0
	v_mov_b32_dpp v122, v110 row_shr:1 row_mask:0xf bank_mask:0xf bound_ctrl:0
	v_mov_b32_dpp v123, v110 row_shr:2 row_mask:0xf bank_mask:0xf bound_ctrl:0
	v_mov_b32_dpp v124, v118 row_ror:1 row_mask:0xf bank_mask:0xf
	v_mov_b32_dpp v125, v118 row_ror:2 row_mask:0xf bank_mask:0xf
	v_cndmask_b32_e64 v118, v122, v124, s[40:41]
	v_cndmask_b32_e64 v122, v125, v123, s[38:39]
	v_mov_b32_dpp v123, v111 row_shr:1 row_mask:0xf bank_mask:0xf bound_ctrl:0
	v_mov_b32_dpp v124, v111 row_shr:2 row_mask:0xf bank_mask:0xf bound_ctrl:0
	v_mov_b32_dpp v125, v119 row_ror:1 row_mask:0xf bank_mask:0xf
	v_mov_b32_dpp v126, v119 row_ror:2 row_mask:0xf bank_mask:0xf
	v_cndmask_b32_e64 v119, v123, v125, s[40:41]
	v_cndmask_b32_e64 v123, v126, v124, s[38:39]
	v_mov_b32_dpp v124, v112 row_shr:1 row_mask:0xf bank_mask:0xf bound_ctrl:0
	v_mov_b32_dpp v125, v112 row_shr:2 row_mask:0xf bank_mask:0xf bound_ctrl:0
	v_mov_b32_dpp v126, v120 row_ror:1 row_mask:0xf bank_mask:0xf
	v_mov_b32_dpp v127, v120 row_ror:2 row_mask:0xf bank_mask:0xf
	v_cndmask_b32_e64 v120, v124, v126, s[40:41]
	v_cndmask_b32_e64 v124, v127, v125, s[38:39]
	v_mov_b32_dpp v125, v113 row_shr:1 row_mask:0xf bank_mask:0xf bound_ctrl:0
	v_mov_b32_dpp v126, v113 row_shr:2 row_mask:0xf bank_mask:0xf bound_ctrl:0
	v_mov_b32_dpp v127, v121 row_ror:1 row_mask:0xf bank_mask:0xf
	v_mov_b32_dpp v128, v121 row_ror:2 row_mask:0xf bank_mask:0xf
	v_cndmask_b32_e64 v121, v125, v127, s[40:41]
	v_cndmask_b32_e64 v125, v128, v126, s[38:39]
	v_pk_mul_f32 v[122:123], v[90:91], v[122:123]
	v_pk_fma_f32 v[118:119], v[94:95], v[118:119], v[122:123]
	v_pk_mul_f32 v[122:123], v[92:93], v[124:125]
	v_pk_fma_f32 v[110:111], v[110:111], v[98:99], v[118:119]
	v_pk_fma_f32 v[120:121], v[96:97], v[120:121], v[122:123]
	v_pk_add_f32 v[110:111], v[102:103], v[110:111]
	v_pk_fma_f32 v[112:113], v[112:113], v[100:101], v[120:121]
	v_pk_mul_f32 v[118:119], v[110:111], v[110:111]
	v_pk_add_f32 v[112:113], v[104:105], v[112:113]
	v_pk_fma_f32 v[118:119], v[118:119], s[78:79], 1.0 op_sel_hi:[1,0,0]
	v_pk_mul_f32 v[120:121], v[112:113], v[112:113]
	v_pk_mul_f32 v[118:119], v[110:111], v[118:119]
	v_pk_fma_f32 v[120:121], v[120:121], s[78:79], 1.0 op_sel_hi:[1,0,0]
	v_pk_mul_f32 v[118:119], v[118:119], s[24:25] op_sel_hi:[1,0]
	v_pk_mul_f32 v[120:121], v[112:113], v[120:121]
	v_exp_f32_e32 v118, v118
	v_exp_f32_e32 v119, v119
	v_pk_mul_f32 v[120:121], v[120:121], s[24:25] op_sel_hi:[1,0]
	v_exp_f32_e32 v120, v120
	v_exp_f32_e32 v121, v121
	v_mov_b32_dpp v126, v106 row_shr:1 row_mask:0xf bank_mask:0xf bound_ctrl:0
	v_mov_b32_dpp v127, v106 row_shr:2 row_mask:0xf bank_mask:0xf bound_ctrl:0
; #define LAS __attribute__((address_space(3)))
; __device__ __forceinline__ u32x4 pack8(const float (&f)[8]) { u32x4 w; w.x = cvt_pk_bf16(f[0], f[1]); w.y = cvt_pk_bf16(f[2], f[3]); w.z = cvt_pk_bf16(f[4], f[5]); w.w = cvt_pk_bf16(f[6], f[7]); return w; }
; __device__ __forceinline__ float dpp_row_shr1(float x) { return __int_as_float(__builtin_amdgcn_update_dpp(0, __float_as_int(x), 0x111, 0xf, 0xf, false)); }
; __device__ __forceinline__ float dpp_row_shr2(float x) { return __int_as_float(__builtin_amdgcn_update_dpp(0, __float_as_int(x), 0x112, 0xf, 0xf, false)); }
;     __device__ __forceinline__ void operator()(const f32x4 (&acc)[2][2][4][2], const Unit& u, int wr, int wc, int fr, int fq) const {
;     ...
;                 if (m == 0) {
;                     if (B > 0) { const LAS float* p = XG + ((B - 1) * 2) * 128 + chl; const f32x4 r0a = *(const LAS f32x4*)p, r0b = *(const LAS f32x4*)(p + 4), r1a = *(const LAS f32x4*)(p + 128), r1b = *(const LAS f32x4*)(p + 132);
; #pragma unroll
;                         for (int j = 0; j < 4; ++j) { q14[j] = r0a[j]; q14[4 + j] = r0b[j]; q15[j] = r1a[j]; q15[4 + j] = r1b[j]; } }
;                     else {
; #pragma unroll
;                         for (int j = 0; j < 8; ++j) { q14[j] = 0.f; q15[j] = 0.f; } }
;     ...
;                     float p1a[8], p2a[8];
; #pragma unroll
;                     for (int e = 0; e < 8; ++e) { const float pv = (e < 4) ? acc[ai][0][m - 1][0][e & 3] : acc[ai][0][m - 1][1][e & 3];
;                         const float s1 = dpp_row_shr1(g8[e]), s2 = dpp_row_shr2(g8[e]), r1 = dpp_row_ror1(pv), r2 = dpp_row_ror2(pv);
;                         p1a[e] = (fr >= 1) ? s1 : r1; p2a[e] = (fr >= 2) ? s2 : r2; }
; #pragma unroll
;                     for (int e = 0; e < 8; e += 2) { const f32x2 gt = (f32x2){w0[e], w0[e + 1]} * (f32x2){p2a[e], p2a[e + 1]} + (f32x2){w1[e], w1[e + 1]} * (f32x2){p1a[e], p1a[e + 1]} + (f32x2){w2[e], w2[e + 1]} * (f32x2){g8[e], g8[e + 1]} + (f32x2){bb[e], bb[e + 1]};
;                         const f32x2 r = gelu_tanh_mul2(gt, (f32x2){u8[e], u8[e + 1]}); o[e] = r.x; o[e + 1] = r.y; }
;                 }
;                 const int rloc = 128 * ai + 64 * wr + 16 * m + fr;
;                 if (!(B == 0 && m == 0 && fr < 2)) *(u32x4*)(ACT + (size_t)(u.pm * BM + rloc) * FF + chg) = pack8(o);
	v_mov_b32_dpp v128, v114 row_ror:1 row_mask:0xf bank_mask:0xf
	v_mov_b32_dpp v129, v114 row_ror:2 row_mask:0xf bank_mask:0xf
	v_cndmask_b32_e64 v114, v126, v128, s[40:41]
	v_cndmask_b32_e64 v126, v129, v127, s[38:39]
	v_pk_add_f32 v[118:119], v[118:119], 1.0 op_sel_hi:[1,0]
	v_mov_b32_dpp v127, v107 row_shr:1 row_mask:0xf bank_mask:0xf bound_ctrl:0
	v_mov_b32_dpp v128, v107 row_shr:2 row_mask:0xf bank_mask:0xf bound_ctrl:0
	v_mov_b32_dpp v129, v115 row_ror:1 row_mask:0xf bank_mask:0xf
	v_mov_b32_dpp v130, v115 row_ror:2 row_mask:0xf bank_mask:0xf
	v_rcp_f32_e32 v118, v118
	v_rcp_f32_e32 v119, v119
	v_pk_add_f32 v[120:121], v[120:121], 1.0 op_sel_hi:[1,0]
	v_cndmask_b32_e64 v115, v127, v129, s[40:41]
	v_cndmask_b32_e64 v127, v130, v128, s[38:39]
	v_rcp_f32_e32 v120, v120
	v_rcp_f32_e32 v121, v121
	v_mov_b32_dpp v128, v108 row_shr:1 row_mask:0xf bank_mask:0xf bound_ctrl:0
	v_mov_b32_dpp v129, v108 row_shr:2 row_mask:0xf bank_mask:0xf bound_ctrl:0
	v_mov_b32_dpp v130, v116 row_ror:1 row_mask:0xf bank_mask:0xf
	v_mov_b32_dpp v131, v116 row_ror:2 row_mask:0xf bank_mask:0xf
	v_cndmask_b32_e64 v116, v128, v130, s[40:41]
	v_cndmask_b32_e64 v128, v131, v129, s[38:39]
	v_mov_b32_dpp v129, v109 row_shr:1 row_mask:0xf bank_mask:0xf bound_ctrl:0
	v_mov_b32_dpp v130, v109 row_shr:2 row_mask:0xf bank_mask:0xf bound_ctrl:0
	v_mov_b32_dpp v131, v117 row_ror:1 row_mask:0xf bank_mask:0xf
	v_mov_b32_dpp v132, v117 row_ror:2 row_mask:0xf bank_mask:0xf
	v_pk_mul_f32 v[110:111], v[110:111], v[118:119]
	v_cndmask_b32_e64 v117, v129, v131, s[40:41]
	v_cndmask_b32_e64 v129, v132, v130, s[38:39]
	v_pk_mul_f32 v[86:87], v[86:87], v[110:111]
	v_pk_mul_f32 v[110:111], v[112:113], v[120:121]
	v_pk_mul_f32 v[112:113], v[66:67], v[126:127]
	v_pk_mul_f32 v[88:89], v[88:89], v[110:111]
	v_pk_fma_f32 v[112:113], v[70:71], v[114:115], v[112:113]
	v_pk_mul_f32 v[114:115], v[68:69], v[128:129]
	v_pk_fma_f32 v[106:107], v[106:107], v[74:75], v[112:113]
	v_pk_fma_f32 v[114:115], v[72:73], v[116:117], v[114:115]
	v_pk_add_f32 v[106:107], v[78:79], v[106:107]
	v_pk_fma_f32 v[108:109], v[108:109], v[76:77], v[114:115]
	v_pk_mul_f32 v[112:113], v[106:107], v[106:107]
	v_pk_add_f32 v[108:109], v[80:81], v[108:109]
	v_pk_fma_f32 v[112:113], v[112:113], s[78:79], 1.0 op_sel_hi:[1,0,0]
	v_pk_mul_f32 v[114:115], v[108:109], v[108:109]
	v_pk_mul_f32 v[112:113], v[106:107], v[112:113]
	v_pk_fma_f32 v[114:115], v[114:115], s[78:79], 1.0 op_sel_hi:[1,0,0]
	v_pk_mul_f32 v[112:113], v[112:113], s[24:25] op_sel_hi:[1,0]
	v_pk_mul_f32 v[114:115], v[108:109], v[114:115]
	v_exp_f32_e32 v112, v112
	v_exp_f32_e32 v113, v113
	v_pk_mul_f32 v[114:115], v[114:115], s[24:25] op_sel_hi:[1,0]
	v_mov_b32_e32 v110, 0
	v_exp_f32_e32 v114, v114
	v_exp_f32_e32 v115, v115
	v_pk_add_f32 v[112:113], v[112:113], 1.0 op_sel_hi:[1,0]
	v_mov_b32_e32 v111, 0
	v_rcp_f32_e32 v112, v112
	v_rcp_f32_e32 v113, v113
	v_pk_add_f32 v[114:115], v[114:115], 1.0 op_sel_hi:[1,0]
	v_pk_mul_f32 v[106:107], v[106:107], v[112:113]
	v_rcp_f32_e32 v114, v114
	v_rcp_f32_e32 v115, v115
	v_pk_mul_f32 v[106:107], v[82:83], v[106:107]
	v_mov_b32_e32 v112, 0
	v_mov_b32_e32 v113, 0
	v_pk_mul_f32 v[82:83], v[108:109], v[114:115]
	s_nop 0
	v_pk_mul_f32 v[108:109], v[84:85], v[82:83]
	v_cvt_pk_bf16_f32 v82, v86, v87
	v_or_b32_e32 v86, 48, v210
	v_mad_i64_i32 v[86:87], s[8:9], v86, s7, v[140:141]
	v_cvt_pk_bf16_f32 v83, v88, v89
	v_cvt_pk_bf16_f32 v84, v106, v107
	v_cvt_pk_bf16_f32 v85, v108, v109
	v_lshl_add_u64 v[86:87], v[86:87], 0, v[138:139]
	global_store_dwordx4 v[86:87], v[82:85], off
	v_mov_b32_e32 v109, 0
	v_mov_b32_e32 v108, 0
	v_mov_b32_e32 v107, 0
	v_mov_b32_e32 v106, 0
	v_mov_b32_e32 v85, 0
	v_mov_b32_e32 v84, 0
	v_mov_b32_e32 v83, 0
	v_mov_b32_e32 v82, 0
	v_mov_b32_e32 v86, 0
	v_mov_b32_e32 v87, 0
	v_mov_b32_e32 v88, 0
	v_mov_b32_e32 v89, 0
	s_cbranch_vccnz .LBB0_86
	ds_read_b128 v[82:85], v207
	ds_read_b128 v[106:109], v207 offset:16
	ds_read_b128 v[86:89], v207 offset:512
	ds_read_b128 v[110:113], v207 offset:528

; __device__ __forceinline__ u32x4 pack8(const float (&f)[8]) { u32x4 w; w.x = cvt_pk_bf16(f[0], f[1]); w.y = cvt_pk_bf16(f[2], f[3]); w.z = cvt_pk_bf16(f[4], f[5]); w.w = cvt_pk_bf16(f[6], f[7]); return w; }
; __device__ __forceinline__ float dpp_row_shr1(float x) { return __int_as_float(__builtin_amdgcn_update_dpp(0, __float_as_int(x), 0x111, 0xf, 0xf, false)); }
; __device__ __forceinline__ float dpp_row_shr2(float x) { return __int_as_float(__builtin_amdgcn_update_dpp(0, __float_as_int(x), 0x112, 0xf, 0xf, false)); }
; __device__ __forceinline__ float dpp_row_ror1(float x) { return __int_as_float(__builtin_amdgcn_update_dpp(0, __float_as_int(x), 0x121, 0xf, 0xf, false)); }
; __device__ __forceinline__ f32x2 gelu_tanh_mul2(f32x2 gt, f32x2 up) {
;     const f32x2 g2 = gt * gt;
;     const f32x2 t = gt * (g2 * 0.044715f + 1.0f);
;     const f32x2 sx = t * (-2.0f * 0.7978845608028654f * 1.4426950408889634f);
;     f32x2 e; e.x = __builtin_amdgcn_exp2f(sx.x); e.y = __builtin_amdgcn_exp2f(sx.y);
;     const f32x2 d = e + 1.0f;
;     f32x2 r; r.x = __builtin_amdgcn_rcpf(d.x); r.y = __builtin_amdgcn_rcpf(d.y);
;     return gt * r * up;
; }
;     __device__ __forceinline__ void operator()(const f32x4 (&acc)[2][2][4][2], const Unit& u, int wr, int wc, int fr, int fq) const {
;     ...
;                     float p1a[8], p2a[8];
; #pragma unroll
;                     for (int e = 0; e < 8; ++e) { const float pv = (e < 4) ? acc[ai][0][m - 1][0][e & 3] : acc[ai][0][m - 1][1][e & 3];
;                         const float s1 = dpp_row_shr1(g8[e]), s2 = dpp_row_shr2(g8[e]), r1 = dpp_row_ror1(pv), r2 = dpp_row_ror2(pv);
;                         p1a[e] = (fr >= 1) ? s1 : r1; p2a[e] = (fr >= 2) ? s2 : r2; }
; #pragma unroll
;                     for (int e = 0; e < 8; e += 2) { const f32x2 gt = (f32x2){w0[e], w0[e + 1]} * (f32x2){p2a[e], p2a[e + 1]} + (f32x2){w1[e], w1[e + 1]} * (f32x2){p1a[e], p1a[e + 1]} + (f32x2){w2[e], w2[e + 1]} * (f32x2){g8[e], g8[e + 1]} + (f32x2){bb[e], bb[e + 1]};
;                         const f32x2 r = gelu_tanh_mul2(gt, (f32x2){u8[e], u8[e + 1]}); o[e] = r.x; o[e + 1] = r.y; }
;                 }
;                 const int rloc = 128 * ai + 64 * wr + 16 * m + fr;
;                 if (!(B == 0 && m == 0 && fr < 2)) *(u32x4*)(ACT + (size_t)(u.pm * BM + rloc) * FF + chg) = pack8(o);
.LBB0_88:
	s_or_b64 exec, exec, s[30:31]
	s_nop 0
	s_nop 0
	s_nop 0
	v_mov_b32_dpp v58, v38 row_shr:1 row_mask:0xf bank_mask:0xf bound_ctrl:0
	v_mov_b32_dpp v59, v38 row_shr:2 row_mask:0xf bank_mask:0xf bound_ctrl:0
	v_mov_b32_dpp v60, v54 row_ror:1 row_mask:0xf bank_mask:0xf
	v_mov_b32_dpp v61, v54 row_ror:2 row_mask:0xf bank_mask:0xf
	v_cndmask_b32_e64 v54, v58, v60, s[40:41]
	v_cndmask_b32_e64 v58, v61, v59, s[38:39]
	v_mov_b32_dpp v59, v39 row_shr:1 row_mask:0xf bank_mask:0xf bound_ctrl:0
	v_mov_b32_dpp v60, v39 row_shr:2 row_mask:0xf bank_mask:0xf bound_ctrl:0
	v_mov_b32_dpp v61, v55 row_ror:1 row_mask:0xf bank_mask:0xf
	v_mov_b32_dpp v62, v55 row_ror:2 row_mask:0xf bank_mask:0xf
	v_cndmask_b32_e64 v55, v59, v61, s[40:41]
	v_cndmask_b32_e64 v59, v62, v60, s[38:39]
	v_mov_b32_dpp v60, v40 row_shr:1 row_mask:0xf bank_mask:0xf bound_ctrl:0
	v_mov_b32_dpp v61, v40 row_shr:2 row_mask:0xf bank_mask:0xf bound_ctrl:0
	v_mov_b32_dpp v62, v56 row_ror:1 row_mask:0xf bank_mask:0xf
	v_mov_b32_dpp v63, v56 row_ror:2 row_mask:0xf bank_mask:0xf
	v_cndmask_b32_e64 v56, v60, v62, s[40:41]
	v_cndmask_b32_e64 v60, v63, v61, s[38:39]
	v_mov_b32_dpp v61, v41 row_shr:1 row_mask:0xf bank_mask:0xf bound_ctrl:0
	v_mov_b32_dpp v62, v41 row_shr:2 row_mask:0xf bank_mask:0xf bound_ctrl:0
	v_mov_b32_dpp v63, v57 row_ror:1 row_mask:0xf bank_mask:0xf
	v_mov_b32_dpp v64, v57 row_ror:2 row_mask:0xf bank_mask:0xf
	v_cndmask_b32_e64 v57, v61, v63, s[40:41]
	v_cndmask_b32_e64 v61, v64, v62, s[38:39]
	v_pk_mul_f32 v[58:59], v[90:91], v[58:59]
	v_pk_mul_f32 v[60:61], v[92:93], v[60:61]
	v_pk_fma_f32 v[54:55], v[94:95], v[54:55], v[58:59]
	v_pk_fma_f32 v[56:57], v[96:97], v[56:57], v[60:61]
	v_pk_fma_f32 v[54:55], v[38:39], v[98:99], v[54:55]
	v_pk_fma_f32 v[56:57], v[40:41], v[100:101], v[56:57]
	v_pk_add_f32 v[54:55], v[102:103], v[54:55]
	v_pk_add_f32 v[56:57], v[104:105], v[56:57]
	v_pk_mul_f32 v[58:59], v[54:55], v[54:55]
	v_pk_mul_f32 v[60:61], v[56:57], v[56:57]
	v_pk_fma_f32 v[58:59], v[58:59], s[78:79], 1.0 op_sel_hi:[1,0,0]
	v_pk_fma_f32 v[60:61], v[60:61], s[78:79], 1.0 op_sel_hi:[1,0,0]
	v_pk_mul_f32 v[58:59], v[54:55], v[58:59]
	v_pk_mul_f32 v[60:61], v[56:57], v[60:61]
	v_pk_mul_f32 v[58:59], v[58:59], s[24:25] op_sel_hi:[1,0]
	v_pk_mul_f32 v[60:61], v[60:61], s[24:25] op_sel_hi:[1,0]
	v_exp_f32_e32 v58, v58
	v_exp_f32_e32 v59, v59
	v_exp_f32_e32 v60, v60
	v_exp_f32_e32 v61, v61
	v_mov_b32_dpp v62, v34 row_shr:1 row_mask:0xf bank_mask:0xf bound_ctrl:0
	v_mov_b32_dpp v63, v34 row_shr:2 row_mask:0xf bank_mask:0xf bound_ctrl:0
	v_mov_b32_dpp v64, v50 row_ror:1 row_mask:0xf bank_mask:0xf
	v_mov_b32_dpp v65, v50 row_ror:2 row_mask:0xf bank_mask:0xf
	v_cndmask_b32_e64 v50, v62, v64, s[40:41]
	v_cndmask_b32_e64 v62, v65, v63, s[38:39]
	s_waitcnt lgkmcnt(3)
	v_pk_add_f32 v[58:59], v[58:59], 1.0 op_sel_hi:[1,0]
	v_mov_b32_dpp v63, v35 row_shr:1 row_mask:0xf bank_mask:0xf bound_ctrl:0
	v_mov_b32_dpp v64, v35 row_shr:2 row_mask:0xf bank_mask:0xf bound_ctrl:0
	v_mov_b32_dpp v65, v51 row_ror:1 row_mask:0xf bank_mask:0xf
	v_mov_b32_dpp v82, v51 row_ror:2 row_mask:0xf bank_mask:0xf
	v_rcp_f32_e32 v58, v58
	v_rcp_f32_e32 v59, v59
	v_pk_add_f32 v[60:61], v[60:61], 1.0 op_sel_hi:[1,0]
	v_cndmask_b32_e64 v51, v63, v65, s[40:41]
	v_cndmask_b32_e64 v63, v82, v64, s[38:39]
	v_rcp_f32_e32 v60, v60
	v_rcp_f32_e32 v61, v61
	v_mov_b32_dpp v64, v36 row_shr:1 row_mask:0xf bank_mask:0xf bound_ctrl:0
	v_mov_b32_dpp v65, v36 row_shr:2 row_mask:0xf bank_mask:0xf bound_ctrl:0
	v_mov_b32_dpp v82, v52 row_ror:1 row_mask:0xf bank_mask:0xf
	v_mov_b32_dpp v83, v52 row_ror:2 row_mask:0xf bank_mask:0xf
	v_cndmask_b32_e64 v52, v64, v82, s[40:41]
	v_cndmask_b32_e64 v64, v83, v65, s[38:39]
	v_mov_b32_dpp v65, v37 row_shr:1 row_mask:0xf bank_mask:0xf bound_ctrl:0
	v_mov_b32_dpp v82, v37 row_shr:2 row_mask:0xf bank_mask:0xf bound_ctrl:0
	v_mov_b32_dpp v83, v53 row_ror:1 row_mask:0xf bank_mask:0xf
	v_mov_b32_dpp v84, v53 row_ror:2 row_mask:0xf bank_mask:0xf
	v_pk_mul_f32 v[54:55], v[54:55], v[58:59]
	v_cndmask_b32_e64 v53, v65, v83, s[40:41]
	v_cndmask_b32_e64 v65, v84, v82, s[38:39]
	v_pk_mul_f32 v[46:47], v[46:47], v[54:55]
	v_pk_mul_f32 v[54:55], v[56:57], v[60:61]
	v_pk_mul_f32 v[56:57], v[66:67], v[62:63]
	v_pk_mul_f32 v[58:59], v[68:69], v[64:65]
	v_pk_fma_f32 v[50:51], v[70:71], v[50:51], v[56:57]
	v_pk_fma_f32 v[52:53], v[72:73], v[52:53], v[58:59]
	v_pk_fma_f32 v[50:51], v[34:35], v[74:75], v[50:51]
	v_pk_fma_f32 v[52:53], v[36:37], v[76:77], v[52:53]
	v_pk_add_f32 v[50:51], v[78:79], v[50:51]
	v_pk_add_f32 v[52:53], v[80:81], v[52:53]
	v_pk_mul_f32 v[56:57], v[50:51], v[50:51]
	v_pk_mul_f32 v[58:59], v[52:53], v[52:53]
	v_pk_fma_f32 v[56:57], v[56:57], s[78:79], 1.0 op_sel_hi:[1,0,0]
	v_pk_fma_f32 v[58:59], v[58:59], s[78:79], 1.0 op_sel_hi:[1,0,0]
	v_pk_mul_f32 v[56:57], v[50:51], v[56:57]
	v_pk_mul_f32 v[58:59], v[52:53], v[58:59]
	v_pk_mul_f32 v[56:57], v[56:57], s[24:25] op_sel_hi:[1,0]
	v_pk_mul_f32 v[58:59], v[58:59], s[24:25] op_sel_hi:[1,0]
	v_exp_f32_e32 v56, v56
	v_exp_f32_e32 v57, v57
	v_exp_f32_e32 v58, v58
	v_exp_f32_e32 v59, v59
	v_readlane_b32 s8, v253, 57
	v_pk_add_f32 v[56:57], v[56:57], 1.0 op_sel_hi:[1,0]
	v_pk_mul_f32 v[48:49], v[48:49], v[54:55]
	v_rcp_f32_e32 v56, v56
	v_rcp_f32_e32 v57, v57
	v_pk_add_f32 v[58:59], v[58:59], 1.0 op_sel_hi:[1,0]
	v_readlane_b32 s9, v253, 58
	v_rcp_f32_e32 v58, v58
	v_rcp_f32_e32 v59, v59
	v_pk_mul_f32 v[50:51], v[50:51], v[56:57]
	v_mov_b32_e32 v54, v195
	v_pk_mul_f32 v[42:43], v[42:43], v[50:51]
	v_pk_mul_f32 v[50:51], v[52:53], v[58:59]
	v_mov_b32_e32 v52, v195
	v_pk_mul_f32 v[50:51], v[44:45], v[50:51]
	v_cvt_pk_bf16_f32 v44, v46, v47
; __device__ __forceinline__ u32x4 pack8(const float (&f)[8]) { u32x4 w; w.x = cvt_pk_bf16(f[0], f[1]); w.y = cvt_pk_bf16(f[2], f[3]); w.z = cvt_pk_bf16(f[4], f[5]); w.w = cvt_pk_bf16(f[6], f[7]); return w; }
; __device__ __forceinline__ float dpp_row_shr1(float x) { return __int_as_float(__builtin_amdgcn_update_dpp(0, __float_as_int(x), 0x111, 0xf, 0xf, false)); }
; __device__ __forceinline__ float dpp_row_shr2(float x) { return __int_as_float(__builtin_amdgcn_update_dpp(0, __float_as_int(x), 0x112, 0xf, 0xf, false)); }
; __device__ __forceinline__ float dpp_row_ror1(float x) { return __int_as_float(__builtin_amdgcn_update_dpp(0, __float_as_int(x), 0x121, 0xf, 0xf, false)); }
; __device__ __forceinline__ f32x2 gelu_tanh_mul2(f32x2 gt, f32x2 up) {
;     const f32x2 g2 = gt * gt;
;     const f32x2 t = gt * (g2 * 0.044715f + 1.0f);
;     const f32x2 sx = t * (-2.0f * 0.7978845608028654f * 1.4426950408889634f);
;     f32x2 e; e.x = __builtin_amdgcn_exp2f(sx.x); e.y = __builtin_amdgcn_exp2f(sx.y);
;     const f32x2 d = e + 1.0f;
;     f32x2 r; r.x = __builtin_amdgcn_rcpf(d.x); r.y = __builtin_amdgcn_rcpf(d.y);
;     return gt * r * up;
; }
;     __device__ __forceinline__ void operator()(const f32x4 (&acc)[2][2][4][2], const Unit& u, int wr, int wc, int fr, int fq) const {
;     ...
;                     float p1a[8], p2a[8];
; #pragma unroll
;                     for (int e = 0; e < 8; ++e) { const float pv = (e < 4) ? acc[ai][0][m - 1][0][e & 3] : acc[ai][0][m - 1][1][e & 3];
;                         const float s1 = dpp_row_shr1(g8[e]), s2 = dpp_row_shr2(g8[e]), r1 = dpp_row_ror1(pv), r2 = dpp_row_ror2(pv);
;                         p1a[e] = (fr >= 1) ? s1 : r1; p2a[e] = (fr >= 2) ? s2 : r2; }
; #pragma unroll
;                     for (int e = 0; e < 8; e += 2) { const f32x2 gt = (f32x2){w0[e], w0[e + 1]} * (f32x2){p2a[e], p2a[e + 1]} + (f32x2){w1[e], w1[e + 1]} * (f32x2){p1a[e], p1a[e + 1]} + (f32x2){w2[e], w2[e + 1]} * (f32x2){g8[e], g8[e + 1]} + (f32x2){bb[e], bb[e + 1]};
;                         const f32x2 r = gelu_tanh_mul2(gt, (f32x2){u8[e], u8[e + 1]}); o[e] = r.x; o[e + 1] = r.y; }
;                 }
;                 const int rloc = 128 * ai + 64 * wr + 16 * m + fr;
;                 if (!(B == 0 && m == 0 && fr < 2)) *(u32x4*)(ACT + (size_t)(u.pm * BM + rloc) * FF + chg) = pack8(o);
	v_cvt_pk_bf16_f32 v45, v48, v49
	v_cvt_pk_bf16_f32 v46, v42, v43
	v_add_u32_e32 v48, 0x90, v210
	v_mov_b64_e32 v[42:43], s[8:9]
	v_mad_i64_i32 v[48:49], s[8:9], v48, s7, v[42:43]
	v_cvt_pk_bf16_f32 v47, v50, v51
	v_lshl_add_u64 v[48:49], v[48:49], 0, v[138:139]
	global_store_dwordx4 v[48:49], v[44:47], off
	s_nop 0
	s_nop 0
	s_nop 0
	s_nop 0
	v_mov_b32_dpp v44, v22 row_shr:1 row_mask:0xf bank_mask:0xf bound_ctrl:0
	v_mov_b32_dpp v45, v22 row_shr:2 row_mask:0xf bank_mask:0xf bound_ctrl:0
	v_mov_b32_dpp v46, v38 row_ror:1 row_mask:0xf bank_mask:0xf
	v_mov_b32_dpp v47, v38 row_ror:2 row_mask:0xf bank_mask:0xf
	v_cndmask_b32_e64 v38, v44, v46, s[40:41]
	v_cndmask_b32_e64 v44, v47, v45, s[38:39]
	v_mov_b32_dpp v45, v23 row_shr:1 row_mask:0xf bank_mask:0xf bound_ctrl:0
	v_mov_b32_dpp v46, v23 row_shr:2 row_mask:0xf bank_mask:0xf bound_ctrl:0
	v_mov_b32_dpp v47, v39 row_ror:1 row_mask:0xf bank_mask:0xf
	v_mov_b32_dpp v48, v39 row_ror:2 row_mask:0xf bank_mask:0xf
	v_cndmask_b32_e64 v39, v45, v47, s[40:41]
	v_cndmask_b32_e64 v45, v48, v46, s[38:39]
	v_mov_b32_dpp v46, v24 row_shr:1 row_mask:0xf bank_mask:0xf bound_ctrl:0
	v_mov_b32_dpp v47, v24 row_shr:2 row_mask:0xf bank_mask:0xf bound_ctrl:0
	v_mov_b32_dpp v48, v40 row_ror:1 row_mask:0xf bank_mask:0xf
	v_mov_b32_dpp v49, v40 row_ror:2 row_mask:0xf bank_mask:0xf
	v_cndmask_b32_e64 v40, v46, v48, s[40:41]
	v_cndmask_b32_e64 v46, v49, v47, s[38:39]
	v_mov_b32_dpp v47, v25 row_shr:1 row_mask:0xf bank_mask:0xf bound_ctrl:0
	v_mov_b32_dpp v48, v25 row_shr:2 row_mask:0xf bank_mask:0xf bound_ctrl:0
	v_mov_b32_dpp v49, v41 row_ror:1 row_mask:0xf bank_mask:0xf
	v_mov_b32_dpp v50, v41 row_ror:2 row_mask:0xf bank_mask:0xf
	v_cndmask_b32_e64 v41, v47, v49, s[40:41]
	v_cndmask_b32_e64 v47, v50, v48, s[38:39]
	v_pk_mul_f32 v[44:45], v[90:91], v[44:45]
	v_pk_mul_f32 v[46:47], v[92:93], v[46:47]
	v_pk_fma_f32 v[38:39], v[94:95], v[38:39], v[44:45]
	v_pk_fma_f32 v[40:41], v[96:97], v[40:41], v[46:47]
	v_pk_fma_f32 v[38:39], v[22:23], v[98:99], v[38:39]
	v_pk_fma_f32 v[40:41], v[24:25], v[100:101], v[40:41]
	v_pk_add_f32 v[38:39], v[102:103], v[38:39]
	v_pk_add_f32 v[40:41], v[104:105], v[40:41]
	v_pk_mul_f32 v[44:45], v[38:39], v[38:39]
	v_pk_mul_f32 v[46:47], v[40:41], v[40:41]
	v_pk_fma_f32 v[44:45], v[44:45], s[78:79], 1.0 op_sel_hi:[1,0,0]
	v_pk_fma_f32 v[46:47], v[46:47], s[78:79], 1.0 op_sel_hi:[1,0,0]
	v_pk_mul_f32 v[44:45], v[38:39], v[44:45]
	v_pk_mul_f32 v[46:47], v[40:41], v[46:47]
	v_pk_mul_f32 v[44:45], v[44:45], s[24:25] op_sel_hi:[1,0]
	v_pk_mul_f32 v[46:47], v[46:47], s[24:25] op_sel_hi:[1,0]
	v_exp_f32_e32 v44, v44
	v_exp_f32_e32 v45, v45
	v_exp_f32_e32 v46, v46
	v_exp_f32_e32 v47, v47
	v_mov_b32_dpp v48, v18 row_shr:1 row_mask:0xf bank_mask:0xf bound_ctrl:0
	v_mov_b32_dpp v49, v18 row_shr:2 row_mask:0xf bank_mask:0xf bound_ctrl:0
	v_mov_b32_dpp v50, v34 row_ror:1 row_mask:0xf bank_mask:0xf
	v_mov_b32_dpp v51, v34 row_ror:2 row_mask:0xf bank_mask:0xf
	v_cndmask_b32_e64 v34, v48, v50, s[40:41]
	v_cndmask_b32_e64 v48, v51, v49, s[38:39]
	v_pk_add_f32 v[44:45], v[44:45], 1.0 op_sel_hi:[1,0]
	v_mov_b32_dpp v49, v19 row_shr:1 row_mask:0xf bank_mask:0xf bound_ctrl:0
	v_mov_b32_dpp v50, v19 row_shr:2 row_mask:0xf bank_mask:0xf bound_ctrl:0
	v_mov_b32_dpp v51, v35 row_ror:1 row_mask:0xf bank_mask:0xf
	v_mov_b32_dpp v52, v35 row_ror:2 row_mask:0xf bank_mask:0xf
	v_rcp_f32_e32 v44, v44
	v_rcp_f32_e32 v45, v45
	v_pk_add_f32 v[46:47], v[46:47], 1.0 op_sel_hi:[1,0]
	v_cndmask_b32_e64 v35, v49, v51, s[40:41]
	v_cndmask_b32_e64 v49, v52, v50, s[38:39]
	v_rcp_f32_e32 v46, v46
	v_rcp_f32_e32 v47, v47
	v_mov_b32_dpp v50, v20 row_shr:1 row_mask:0xf bank_mask:0xf bound_ctrl:0
	v_mov_b32_dpp v51, v20 row_shr:2 row_mask:0xf bank_mask:0xf bound_ctrl:0
	v_mov_b32_dpp v52, v36 row_ror:1 row_mask:0xf bank_mask:0xf
	v_mov_b32_dpp v53, v36 row_ror:2 row_mask:0xf bank_mask:0xf
	v_cndmask_b32_e64 v36, v50, v52, s[40:41]
	v_cndmask_b32_e64 v50, v53, v51, s[38:39]
	v_mov_b32_dpp v51, v21 row_shr:1 row_mask:0xf bank_mask:0xf bound_ctrl:0
	v_mov_b32_dpp v52, v21 row_shr:2 row_mask:0xf bank_mask:0xf bound_ctrl:0
	v_mov_b32_dpp v53, v37 row_ror:1 row_mask:0xf bank_mask:0xf
	v_mov_b32_dpp v54, v37 row_ror:2 row_mask:0xf bank_mask:0xf
	v_pk_mul_f32 v[38:39], v[38:39], v[44:45]
	v_cndmask_b32_e64 v37, v51, v53, s[40:41]
	v_cndmask_b32_e64 v51, v54, v52, s[38:39]
	v_pk_mul_f32 v[30:31], v[30:31], v[38:39]
	v_pk_mul_f32 v[38:39], v[40:41], v[46:47]
	v_pk_mul_f32 v[40:41], v[66:67], v[48:49]
	v_pk_mul_f32 v[44:45], v[68:69], v[50:51]
	v_pk_fma_f32 v[34:35], v[70:71], v[34:35], v[40:41]
	v_pk_fma_f32 v[36:37], v[72:73], v[36:37], v[44:45]
	v_pk_fma_f32 v[34:35], v[18:19], v[74:75], v[34:35]
	v_pk_fma_f32 v[36:37], v[20:21], v[76:77], v[36:37]
	v_pk_add_f32 v[34:35], v[78:79], v[34:35]
	v_pk_add_f32 v[36:37], v[80:81], v[36:37]
	v_pk_mul_f32 v[40:41], v[34:35], v[34:35]
	v_pk_mul_f32 v[44:45], v[36:37], v[36:37]
	v_pk_fma_f32 v[40:41], v[40:41], s[78:79], 1.0 op_sel_hi:[1,0,0]
	v_pk_fma_f32 v[44:45], v[44:45], s[78:79], 1.0 op_sel_hi:[1,0,0]
	v_pk_mul_f32 v[40:41], v[34:35], v[40:41]
	v_pk_mul_f32 v[44:45], v[36:37], v[44:45]
	v_pk_mul_f32 v[40:41], v[40:41], s[24:25] op_sel_hi:[1,0]
	v_pk_mul_f32 v[44:45], v[44:45], s[24:25] op_sel_hi:[1,0]
	v_exp_f32_e32 v40, v40
	v_exp_f32_e32 v41, v41
	v_exp_f32_e32 v44, v44
	v_exp_f32_e32 v45, v45
	v_pk_mul_f32 v[32:33], v[32:33], v[38:39]
	v_pk_add_f32 v[40:41], v[40:41], 1.0 op_sel_hi:[1,0]
	s_andn2_b64 vcc, exec, s[44:45]
	v_rcp_f32_e32 v40, v40
	v_rcp_f32_e32 v41, v41
	v_pk_add_f32 v[44:45], v[44:45], 1.0 op_sel_hi:[1,0]
	s_mov_b64 s[30:31], -1
	v_rcp_f32_e32 v44, v44
	v_rcp_f32_e32 v45, v45
; __device__ __forceinline__ u32x4 pack8(const float (&f)[8]) { u32x4 w; w.x = cvt_pk_bf16(f[0], f[1]); w.y = cvt_pk_bf16(f[2], f[3]); w.z = cvt_pk_bf16(f[4], f[5]); w.w = cvt_pk_bf16(f[6], f[7]); return w; }
; #define PG8_BAR __builtin_amdgcn_s_barrier()
; __device__ __forceinline__ float dpp_row_shr1(float x) { return __int_as_float(__builtin_amdgcn_update_dpp(0, __float_as_int(x), 0x111, 0xf, 0xf, false)); }
; template <class Epi>
; __device__ __forceinline__ void gemm_phase(LAS unsigned char* lds, const Gemm g, const Order& S, const Epi& E) {
;     ...
;         if (wr == 0) PG8_BAR;
;         if constexpr (!Epi::AFTER_DRAIN) E(acc, cur, wr, wc, fr, fq);
;         if (!has_next) break;
;         if constexpr (!Epi::KEEP_ACC) {
; #pragma unroll
;         for (int a = 0; a < 2; ++a)
; #pragma unroll
;             for (int b = 0; b < 2; ++b)
; #pragma unroll
;                 for (int m = 0; m < 4; ++m)
; #pragma unroll
;                     for (int n = 0; n < 2; ++n) acc[a][b][m][n] = (f32x4){0.f, 0.f, 0.f, 0.f};
;         }
;         cur = nxt; cA = nA; cB = nB; ++ui;
;         if (wr == 1) PG8_BAR;
;     __device__ __forceinline__ void operator()(const f32x4 (&acc)[2][2][4][2], const Unit& u, int wr, int wc, int fr, int fq) const {
;     ...
;                     float p1a[8], p2a[8];
; #pragma unroll
;                     for (int e = 0; e < 8; ++e) { const float pv = (e < 4) ? acc[ai][0][m - 1][0][e & 3] : acc[ai][0][m - 1][1][e & 3];
;                         const float s1 = dpp_row_shr1(g8[e]), s2 = dpp_row_shr2(g8[e]), r1 = dpp_row_ror1(pv), r2 = dpp_row_ror2(pv);
;                         p1a[e] = (fr >= 1) ? s1 : r1; p2a[e] = (fr >= 2) ? s2 : r2; }
; #pragma unroll
;                     for (int e = 0; e < 8; e += 2) { const f32x2 gt = (f32x2){w0[e], w0[e + 1]} * (f32x2){p2a[e], p2a[e + 1]} + (f32x2){w1[e], w1[e + 1]} * (f32x2){p1a[e], p1a[e + 1]} + (f32x2){w2[e], w2[e + 1]} * (f32x2){g8[e], g8[e + 1]} + (f32x2){bb[e], bb[e + 1]};
;                         const f32x2 r = gelu_tanh_mul2(gt, (f32x2){u8[e], u8[e + 1]}); o[e] = r.x; o[e + 1] = r.y; }
;                 }
;                 const int rloc = 128 * ai + 64 * wr + 16 * m + fr;
;                 if (!(B == 0 && m == 0 && fr < 2)) *(u32x4*)(ACT + (size_t)(u.pm * BM + rloc) * FF + chg) = pack8(o);
	v_pk_mul_f32 v[34:35], v[34:35], v[40:41]
	s_nop 0
	v_pk_mul_f32 v[34:35], v[26:27], v[34:35]
	v_pk_mul_f32 v[26:27], v[36:37], v[44:45]
	s_nop 0
	v_pk_mul_f32 v[36:37], v[28:29], v[26:27]
	v_cvt_pk_bf16_f32 v26, v30, v31
	v_add_u32_e32 v30, 0xa0, v210
	v_mad_i64_i32 v[30:31], s[8:9], v30, s7, v[42:43]
	v_cvt_pk_bf16_f32 v27, v32, v33
	v_cvt_pk_bf16_f32 v28, v34, v35
	v_cvt_pk_bf16_f32 v29, v36, v37
	v_lshl_add_u64 v[30:31], v[30:31], 0, v[138:139]
	global_store_dwordx4 v[30:31], v[26:29], off
	s_nop 0
	s_nop 0
	s_nop 0
	s_nop 0
	v_mov_b32_dpp v26, v14 row_shr:1 row_mask:0xf bank_mask:0xf bound_ctrl:0
	v_mov_b32_dpp v27, v14 row_shr:2 row_mask:0xf bank_mask:0xf bound_ctrl:0
	v_mov_b32_dpp v28, v22 row_ror:1 row_mask:0xf bank_mask:0xf
	v_mov_b32_dpp v29, v22 row_ror:2 row_mask:0xf bank_mask:0xf
	v_cndmask_b32_e64 v22, v26, v28, s[40:41]
	v_cndmask_b32_e64 v26, v29, v27, s[38:39]
	v_mov_b32_dpp v27, v15 row_shr:1 row_mask:0xf bank_mask:0xf bound_ctrl:0
	v_mov_b32_dpp v28, v15 row_shr:2 row_mask:0xf bank_mask:0xf bound_ctrl:0
	v_mov_b32_dpp v29, v23 row_ror:1 row_mask:0xf bank_mask:0xf
	v_mov_b32_dpp v30, v23 row_ror:2 row_mask:0xf bank_mask:0xf
	v_cndmask_b32_e64 v23, v27, v29, s[40:41]
	v_cndmask_b32_e64 v27, v30, v28, s[38:39]
	v_mov_b32_dpp v28, v16 row_shr:1 row_mask:0xf bank_mask:0xf bound_ctrl:0
	v_mov_b32_dpp v29, v16 row_shr:2 row_mask:0xf bank_mask:0xf bound_ctrl:0
	v_mov_b32_dpp v30, v24 row_ror:1 row_mask:0xf bank_mask:0xf
	v_mov_b32_dpp v31, v24 row_ror:2 row_mask:0xf bank_mask:0xf
	v_cndmask_b32_e64 v24, v28, v30, s[40:41]
	v_cndmask_b32_e64 v28, v31, v29, s[38:39]
	v_mov_b32_dpp v29, v17 row_shr:1 row_mask:0xf bank_mask:0xf bound_ctrl:0
	v_mov_b32_dpp v30, v17 row_shr:2 row_mask:0xf bank_mask:0xf bound_ctrl:0
	v_mov_b32_dpp v31, v25 row_ror:1 row_mask:0xf bank_mask:0xf
	v_mov_b32_dpp v32, v25 row_ror:2 row_mask:0xf bank_mask:0xf
	v_cndmask_b32_e64 v25, v29, v31, s[40:41]
	v_cndmask_b32_e64 v29, v32, v30, s[38:39]
	v_pk_mul_f32 v[26:27], v[90:91], v[26:27]
	v_pk_fma_f32 v[22:23], v[94:95], v[22:23], v[26:27]
	v_pk_mul_f32 v[26:27], v[92:93], v[28:29]
	v_pk_fma_f32 v[14:15], v[14:15], v[98:99], v[22:23]
	v_pk_fma_f32 v[24:25], v[96:97], v[24:25], v[26:27]
	v_pk_add_f32 v[14:15], v[102:103], v[14:15]
	v_pk_fma_f32 v[16:17], v[16:17], v[100:101], v[24:25]
	v_pk_mul_f32 v[22:23], v[14:15], v[14:15]
	v_pk_add_f32 v[16:17], v[104:105], v[16:17]
	v_pk_fma_f32 v[22:23], v[22:23], s[78:79], 1.0 op_sel_hi:[1,0,0]
	v_pk_mul_f32 v[24:25], v[16:17], v[16:17]
	v_pk_mul_f32 v[22:23], v[14:15], v[22:23]
	v_pk_fma_f32 v[24:25], v[24:25], s[78:79], 1.0 op_sel_hi:[1,0,0]
	v_pk_mul_f32 v[22:23], v[22:23], s[24:25] op_sel_hi:[1,0]
	v_pk_mul_f32 v[24:25], v[16:17], v[24:25]
	v_exp_f32_e32 v22, v22
	v_exp_f32_e32 v23, v23
	v_pk_mul_f32 v[24:25], v[24:25], s[24:25] op_sel_hi:[1,0]
	v_exp_f32_e32 v24, v24
	v_exp_f32_e32 v25, v25
	v_mov_b32_dpp v30, v10 row_shr:1 row_mask:0xf bank_mask:0xf bound_ctrl:0
	v_mov_b32_dpp v31, v10 row_shr:2 row_mask:0xf bank_mask:0xf bound_ctrl:0
	v_mov_b32_dpp v32, v18 row_ror:1 row_mask:0xf bank_mask:0xf
	v_mov_b32_dpp v33, v18 row_ror:2 row_mask:0xf bank_mask:0xf
	v_cndmask_b32_e64 v18, v30, v32, s[40:41]
	v_cndmask_b32_e64 v30, v33, v31, s[38:39]
	v_pk_add_f32 v[22:23], v[22:23], 1.0 op_sel_hi:[1,0]
	v_mov_b32_dpp v31, v11 row_shr:1 row_mask:0xf bank_mask:0xf bound_ctrl:0
	v_mov_b32_dpp v32, v11 row_shr:2 row_mask:0xf bank_mask:0xf bound_ctrl:0
	v_mov_b32_dpp v33, v19 row_ror:1 row_mask:0xf bank_mask:0xf
	v_mov_b32_dpp v34, v19 row_ror:2 row_mask:0xf bank_mask:0xf
	v_rcp_f32_e32 v22, v22
	v_rcp_f32_e32 v23, v23
	v_pk_add_f32 v[24:25], v[24:25], 1.0 op_sel_hi:[1,0]
	v_cndmask_b32_e64 v19, v31, v33, s[40:41]
	v_cndmask_b32_e64 v31, v34, v32, s[38:39]
	v_rcp_f32_e32 v24, v24
	v_rcp_f32_e32 v25, v25
	v_mov_b32_dpp v32, v12 row_shr:1 row_mask:0xf bank_mask:0xf bound_ctrl:0
	v_mov_b32_dpp v33, v12 row_shr:2 row_mask:0xf bank_mask:0xf bound_ctrl:0
	v_mov_b32_dpp v34, v20 row_ror:1 row_mask:0xf bank_mask:0xf
	v_mov_b32_dpp v35, v20 row_ror:2 row_mask:0xf bank_mask:0xf
	v_cndmask_b32_e64 v20, v32, v34, s[40:41]
	v_cndmask_b32_e64 v32, v35, v33, s[38:39]
	v_mov_b32_dpp v33, v13 row_shr:1 row_mask:0xf bank_mask:0xf bound_ctrl:0
	v_mov_b32_dpp v34, v13 row_shr:2 row_mask:0xf bank_mask:0xf bound_ctrl:0
	v_mov_b32_dpp v35, v21 row_ror:1 row_mask:0xf bank_mask:0xf
	v_mov_b32_dpp v36, v21 row_ror:2 row_mask:0xf bank_mask:0xf
	v_pk_mul_f32 v[14:15], v[14:15], v[22:23]
	v_cndmask_b32_e64 v21, v33, v35, s[40:41]
	v_cndmask_b32_e64 v33, v36, v34, s[38:39]
	v_pk_mul_f32 v[6:7], v[6:7], v[14:15]
	v_pk_mul_f32 v[14:15], v[16:17], v[24:25]
	v_pk_mul_f32 v[16:17], v[66:67], v[30:31]
	v_pk_mul_f32 v[8:9], v[8:9], v[14:15]
	v_pk_fma_f32 v[16:17], v[70:71], v[18:19], v[16:17]
	v_pk_mul_f32 v[18:19], v[68:69], v[32:33]
	v_pk_fma_f32 v[10:11], v[10:11], v[74:75], v[16:17]
	v_pk_fma_f32 v[18:19], v[72:73], v[20:21], v[18:19]
	v_pk_add_f32 v[10:11], v[78:79], v[10:11]
	v_pk_fma_f32 v[12:13], v[12:13], v[76:77], v[18:19]
	v_pk_mul_f32 v[16:17], v[10:11], v[10:11]
	v_pk_add_f32 v[12:13], v[80:81], v[12:13]
	v_pk_fma_f32 v[16:17], v[16:17], s[78:79], 1.0 op_sel_hi:[1,0,0]
	v_pk_mul_f32 v[18:19], v[12:13], v[12:13]
	v_pk_mul_f32 v[16:17], v[10:11], v[16:17]
	v_pk_fma_f32 v[18:19], v[18:19], s[78:79], 1.0 op_sel_hi:[1,0,0]
	v_pk_mul_f32 v[16:17], v[16:17], s[24:25] op_sel_hi:[1,0]
	v_pk_mul_f32 v[18:19], v[12:13], v[18:19]
	v_exp_f32_e32 v16, v16
	v_exp_f32_e32 v17, v17
	v_pk_mul_f32 v[18:19], v[18:19], s[24:25] op_sel_hi:[1,0]
	v_pk_add_f32 v[16:17], v[16:17], 1.0 op_sel_hi:[1,0]
	v_exp_f32_e32 v18, v18
	v_exp_f32_e32 v19, v19
	v_rcp_f32_e32 v16, v16
	v_rcp_f32_e32 v17, v17
	v_pk_add_f32 v[18:19], v[18:19], 1.0 op_sel_hi:[1,0]
	s_nop 0
	v_rcp_f32_e32 v18, v18
	v_rcp_f32_e32 v19, v19
	v_pk_mul_f32 v[10:11], v[10:11], v[16:17]
	s_nop 0
	v_pk_mul_f32 v[10:11], v[2:3], v[10:11]
	v_pk_mul_f32 v[2:3], v[12:13], v[18:19]
	s_nop 0
	v_pk_mul_f32 v[12:13], v[4:5], v[2:3]
	v_cvt_pk_bf16_f32 v2, v6, v7
	v_add_u32_e32 v6, 0xb0, v210
	v_mad_i64_i32 v[6:7], s[8:9], v6, s7, v[42:43]
	v_lshl_add_u64 v[6:7], v[6:7], 0, v[138:139]
	v_cvt_pk_bf16_f32 v3, v8, v9
	v_cvt_pk_bf16_f32 v4, v10, v11
	v_cvt_pk_bf16_f32 v5, v12, v13
	global_store_dwordx4 v[6:7], v[2:5], off
	s_cbranch_vccnz .LBB0_67
	s_and_b64 vcc, exec, s[46:47]
	s_cbranch_vccnz .LBB0_66
	s_barrier
	s_branch .LBB0_66
